# selected-loop tail: next-tile search and loads before the barrier; loop header: wave-uniform tile-needed tests as scalar bit tests instead of VALU chains + vcc branches
# speedup vs baseline: 1.0926x; 1.0056x over previous
; DI void nsa_item(int wv0, PP p, int item, unsigned char* smem) {
;     ...
;       while (jc >= 0) {
;         const int bn = bc == 2 ? 0 : bc + 1, bn2 = bn == 2 ? 0 : bn + 1;
;         const bool needn = j1 >= 0 && bit128(wlo, whi, j1);
;         if (needn) {
;           const bool seln = bit128(mlo, mhi, j1);
;           const bool on = seln || j1 == i;
;           flash_s3(sK + bn * 9216, qf, on ? m[0] : -1e30f, on ? m[1] : -1e30f, sn_, lane);
;         }
;         if (bit128(wlo, whi, jc)) {
;           if (jc == i) {
;             const bool sel = bit128(mlo, mhi, jc);
;             auto ok = [&](int kt, int ii) { return sel && (16 * kt + 4 * lg + ii) <= qloc; };
;             flash_pv3<true>(sV + bc * 9216, sc_, O, l, ok, lane);
;           } else {
;             flash_pv3<false>(sV + bc * 9216, sc_, O, l, nomask, lane);
;           }
;         }
.LBB0_879:
	s_add_i32 s36, s45, 1
	s_cmp_lg_u32 s45, 2
	s_cselect_b32 s44, s36, 0
	s_cmp_lt_i32 s42, 0
	s_cselect_b64 s[38:39], -1, 0
	s_and_b64 vcc, exec, s[38:39]
	s_cbranch_vccnz .Lmy_selC_old882
	v_readfirstlane_b32 s36, v130
	v_readfirstlane_b32 s37, v131
	v_readfirstlane_b32 s40, v134
	v_readfirstlane_b32 s41, v135
	s_cmp_lt_u32 s42, 64
	s_cselect_b64 vcc, s[36:37], s[40:41]
	s_lshr_b64 vcc, vcc, s42
	s_bitcmp1_b32 vcc_lo, 0
	s_cbranch_scc0 .Lmy_selC_old882
	s_cmp_eq_u32 s85, s33
	s_cbranch_scc1 .Lmy_selC_old
	s_cmp_lt_u32 s85, 64
	s_cselect_b64 vcc, s[36:37], s[40:41]
	s_lshr_b64 vcc, vcc, s85
	s_bitcmp1_b32 vcc_lo, 0
	s_cbranch_scc1 .Lmy_selC_disp
.Lmy_selC_old:
	v_sub_co_u32_e64 v2, s[36:37], s42, 64
	s_cmp_eq_u32 s32, 0
	s_cbranch_scc1 .Lmy_selC_old2
	v_mov_b64_e32 v[108:109], v[96:97]
	v_mov_b64_e32 v[112:113], v[92:93]
	v_mov_b64_e32 v[116:117], v[88:89]
	v_mov_b64_e32 v[128:129], v[84:85]
	v_mov_b64_e32 v[124:125], v[80:81]
	v_mov_b64_e32 v[120:121], v[76:77]
	v_mov_b64_e32 v[104:105], v[72:73]
	v_mov_b64_e32 v[100:101], v[68:69]
	v_mov_b64_e32 v[106:107], v[94:95]
	v_mov_b64_e32 v[110:111], v[90:91]
	v_mov_b64_e32 v[114:115], v[86:87]
	v_mov_b64_e32 v[126:127], v[82:83]
	v_mov_b64_e32 v[122:123], v[78:79]
	v_mov_b64_e32 v[118:119], v[74:75]
	v_mov_b64_e32 v[102:103], v[70:71]
	v_mov_b64_e32 v[98:99], v[66:67]

; #define ISSUE_TILE(RK, RV, T, LDV)                                                   \
;   {                                                                                  \
;     pk0 = BLOAD(RK, koff, (T)*8192);                                                 \
;     pv0 = BLOAD(RV, ((LDV) == 512) ? voffc : voffs, (T)*128);                        \
;   }
; DI void nsa_item(int wv0, PP p, int item, unsigned char* smem) {
;     ...
;         if (j2 >= 0) COMMIT_BUF(bn2)
;         __syncthreads();
;         jc = j1;
;         j1 = j2;
;         bc = bn;
;         if (j1 >= 0) {
;           j2 = next_bit(blo, bhi, j1 + 1);
;           if (j2 >= 0) ISSUE_TILE(rK, rV, j2, S_)
;         } else {
;           j2 = -1;
;         }
.LBB0_887:
.LBB0_888:
	s_cmp_lt_i32 s43, 0
	s_mov_b32 s40, -1
	s_cbranch_scc1 .Lmy_tail_bar
	s_mul_i32 s40, s44, 0x2400
	s_addk_i32 s40, 0x2400
	s_cmp_lg_u32 s44, 2
	s_cselect_b32 s40, s40, 0
	v_lshl_add_u32 v0, s40, 1, v154
	s_waitcnt vmcnt(1)
	ds_write_b128 v0, v[24:27]
	s_waitcnt vmcnt(0)
	ds_write_b128 v0, v[62:65] offset:9216
	s_add_i32 s41, s43, 1
	s_cmp_gt_u32 s43, 62
	s_cselect_b64 s[36:37], -1, 0
	s_and_b64 vcc, exec, s[36:37]
	s_cbranch_vccnz .LBB0_893
	s_lshl_b64 s[36:37], -1, s41
	s_and_b64 s[40:41], s[36:37], s[92:93]
	s_cmp_eq_u64 s[40:41], 0
	s_cselect_b64 s[36:37], -1, 0
	s_ff1_i32_b64 s40, s[40:41]
	s_mov_b32 s41, 64
	s_andn2_b64 vcc, exec, s[36:37]
	s_cbranch_vccz .LBB0_894
	s_branch .LBB0_896

; #define ISSUE_TILE(RK, RV, T, LDV)                                                   \
;   {                                                                                  \
;     pk0 = BLOAD(RK, koff, (T)*8192);                                                 \
;     pv0 = BLOAD(RV, ((LDV) == 512) ? voffc : voffs, (T)*128);                        \
;   }
; DI void nsa_item(int wv0, PP p, int item, unsigned char* smem) {
;     ...
;         if (j2 >= 0) COMMIT_BUF(bn2)
;         __syncthreads();
;         jc = j1;
;         j1 = j2;
;         bc = bn;
;         if (j1 >= 0) {
;           j2 = next_bit(blo, bhi, j1 + 1);
;           if (j2 >= 0) ISSUE_TILE(rK, rV, j2, S_)
;         } else {
;           j2 = -1;
;         }
; #pragma unroll
;         for (int a = 0; a < 2; ++a)
; #pragma unroll
;           for (int c = 0; c < 4; ++c) sc_[a][c] = sn_[a][c];
;       }
.Lmy_tail_bar:
	s_waitcnt lgkmcnt(0)
	s_barrier
	s_and_b64 vcc, exec, s[38:39]
	s_cbranch_vccz .LBB0_878
	s_branch .LBB0_899

; DI f32x4 mfma16(bf16x8 a, bf16x8 b, f32x4 c) { return __builtin_amdgcn_mfma_f32_16x16x32_bf16(a, b, c, 0, 0, 0); }
; DI void flash_s3(const u16* sK, const bf16x8 (&qf)[2][2], float si0, float si1, f32x4 (&s)[2][4], int lane) {
;   const int l15 = lane & 15, lg = lane >> 4;
;   bf16x8 kf[4][2];
; #pragma unroll
;   for (int kt = 0; kt < 4; ++kt)
; #pragma unroll
;     for (int ks = 0; ks < 2; ++ks) kf[kt][ks] = *(const bf16x8*)(sK + (16 * kt + l15) * 72 + ks * 32 + lg * 8);
; #pragma unroll
;   for (int qt = 0; qt < 2; ++qt) {
;     const float si = qt ? si1 : si0;
; #pragma unroll
;     for (int kt = 0; kt < 4; ++kt) {
;       s[qt][kt] = f32x4{si, si, si, si};
; #pragma unroll
;       for (int ks = 0; ks < 2; ++ks) s[qt][kt] = mfma16(kf[kt][ks], qf[qt][ks], s[qt][kt]);
;     }
;   }
; }
; template <bool MASKED, class MaskF>
; DI void flash_pv3(const u16* sV, const f32x4 (&s)[2][4], f32x4 (&O)[2][4], float (&l)[2], MaskF ok, int lane) {
;   const int l15 = lane & 15, lg = lane >> 4;
;   union PFrag { unsigned u[4]; bf16x8 v; };
;   PFrag pf[2][2];
; #pragma unroll
;   for (int qt = 0; qt < 2; ++qt) {
;     float pr[4][4];
;     float rs = 0.f;
; #pragma unroll
;     for (int kt = 0; kt < 4; ++kt)
; #pragma unroll
;       for (int i = 0; i < 4; ++i) {
;         float pv = __builtin_amdgcn_exp2f(s[qt][kt][i]);
;         if (MASKED) pv = ok(kt, i) ? pv : 0.f;
;         pr[kt][i] = pv;
;         rs += pv;
;       }
;     l[qt] += rs;
; #pragma unroll
;     for (int ks2 = 0; ks2 < 2; ++ks2) {
;       pf[qt][ks2].u[0] = pk2(pr[2 * ks2][0], pr[2 * ks2][1]);
;       pf[qt][ks2].u[1] = pk2(pr[2 * ks2][2], pr[2 * ks2][3]);
;       pf[qt][ks2].u[2] = pk2(pr[2 * ks2 + 1][0], pr[2 * ks2 + 1][1]);
;       pf[qt][ks2].u[3] = pk2(pr[2 * ks2 + 1][2], pr[2 * ks2 + 1][3]);
;     }
;   }
; #pragma unroll
;   for (int ks2 = 0; ks2 < 2; ++ks2) {
; #pragma unroll
;     for (int dt = 0; dt < 4; ++dt) {
;       union { uint2 h[2]; bf16x8 v; } vf;
;       vf.h[0] = *(const uint2*)(sV + (16 * dt + l15) * 72 + 32 * ks2 + 4 * lg);
;       vf.h[1] = *(const uint2*)(sV + (16 * dt + l15) * 72 + 32 * ks2 + 16 + 4 * lg);
;       O[0][dt] = mfma16(vf.v, pf[0][ks2].v, O[0][dt]);
;       O[1][dt] = mfma16(vf.v, pf[1][ks2].v, O[1][dt]);
;     }
;   }
; }
.Lmy_selC_fastA:
	v_lshrrev_b64 v[186:187], s42, v[20:21]
	v_lshrrev_b64 v[2:3], s42, v[22:23]
	s_cmp_lt_u32 s42, 64
	s_cselect_b64 s[36:37], -1, 0
	v_cndmask_b32_e64 v0, v2, v186, s[36:37]
	v_and_b32_e32 v0, 1, v0
	s_mul_i32 s36, s44, 0x4800
	v_cmp_eq_u32_e32 vcc, 1, v0
	v_add_u32_e32 v0, s36, v158
	v_lshl_add_u32 v2, v28, 1, v0
	ds_read_b128 v[82:85], v2
	ds_read_b128 v[86:89], v2 offset:64
	s_cmp_eq_u32 s42, s33
	ds_read_b128 v[90:93], v2 offset:2304
	ds_read_b128 v[94:97], v2 offset:2368
	s_cselect_b64 s[36:37], -1, 0
	s_or_b64 s[36:37], vcc, s[36:37]
	v_cndmask_b32_e64 v78, v148, -v29, s[36:37]
	v_lshl_add_u32 v0, v164, 1, v0
	v_cndmask_b32_e64 v182, v148, -v161, s[36:37]
	ds_read_b128 v[166:169], v2 offset:4608
	ds_read_b128 v[170:173], v2 offset:4672
	ds_read_b128 v[174:177], v0
	ds_read_b128 v[178:181], v0 offset:64
	v_mov_b32_e32 v79, v78
	v_mov_b32_e32 v80, v78
	v_mov_b32_e32 v81, v78
	v_mov_b32_e32 v183, v182
	v_mov_b32_e32 v184, v182
	v_mov_b32_e32 v185, v182
	s_mulk_i32 s45, 0x4800
	v_lshlrev_b32_e32 v160, 1, v28
	v_lshlrev_b32_e32 v3, 1, v164
	s_add_i32 s40, s45, 32
	v_add3_u32 v198, s40, v160, v159
	v_add3_u32 v206, s40, v3, v159
	v_add_u32_e32 v214, 0x2000, v198
	v_add_u32_e32 v215, 0x2800, v198
	v_add_u32_e32 v216, 0x3000, v198
	v_add_u32_e32 v217, 0x2000, v206
	v_exp_f32_e32 v98, v98
	v_exp_f32_e32 v99, v99
	v_exp_f32_e32 v100, v100
	v_exp_f32_e32 v101, v101
	v_exp_f32_e32 v102, v102
	v_exp_f32_e32 v103, v103
	s_waitcnt lgkmcnt(7)
	v_mfma_f32_16x16x32_bf16 v[66:69], v[82:85], v[4:7], v[78:81]
	v_exp_f32_e32 v104, v104
	v_mfma_f32_16x16x32_bf16 v[82:85], v[82:85], v[12:15], v[182:185]
	v_exp_f32_e32 v105, v105
	s_waitcnt lgkmcnt(6)
	v_mfma_f32_16x16x32_bf16 v[66:69], v[86:89], v[8:11], v[66:69]
	ds_read_b64 v[198:199], v214 offset:1024
	ds_read_b64 v[200:201], v214 offset:1056
	ds_read_b64 v[202:203], v215 offset:1280
	ds_read_b64 v[204:205], v215 offset:1312
	ds_read_b64 v[206:207], v216 offset:1536
	ds_read_b64 v[208:209], v216 offset:1568
	ds_read_b64 v[210:211], v217 offset:1024
	ds_read_b64 v[212:213], v217 offset:1056
	v_exp_f32_e32 v118, v118
	v_exp_f32_e32 v119, v119
	s_waitcnt lgkmcnt(13)
	v_mfma_f32_16x16x32_bf16 v[70:73], v[90:93], v[4:7], v[78:81]
	v_exp_f32_e32 v120, v120
	v_mfma_f32_16x16x32_bf16 v[82:85], v[86:89], v[16:19], v[82:85]
	v_exp_f32_e32 v121, v121
	v_mfma_f32_16x16x32_bf16 v[86:89], v[90:93], v[12:15], v[182:185]
	v_exp_f32_e32 v122, v122
	v_exp_f32_e32 v123, v123
	s_waitcnt lgkmcnt(12)
	v_mfma_f32_16x16x32_bf16 v[70:73], v[94:97], v[8:11], v[70:73]
	v_exp_f32_e32 v124, v124
	v_exp_f32_e32 v125, v125
	s_waitcnt lgkmcnt(11)
	v_mfma_f32_16x16x32_bf16 v[74:77], v[166:169], v[4:7], v[78:81]
	v_exp_f32_e32 v126, v126
	v_exp_f32_e32 v127, v127
	s_waitcnt lgkmcnt(9)
	v_mfma_f32_16x16x32_bf16 v[78:81], v[174:177], v[4:7], v[78:81]
	v_exp_f32_e32 v128, v128
	v_mfma_f32_16x16x32_bf16 v[86:89], v[94:97], v[16:19], v[86:89]
	v_exp_f32_e32 v129, v129
	v_mfma_f32_16x16x32_bf16 v[90:93], v[166:169], v[12:15], v[182:185]
	v_exp_f32_e32 v114, v114
	v_mfma_f32_16x16x32_bf16 v[94:97], v[174:177], v[12:15], v[182:185]
	v_exp_f32_e32 v115, v115
	v_mfma_f32_16x16x32_bf16 v[74:77], v[170:173], v[8:11], v[74:77]
	v_exp_f32_e32 v116, v116
	v_exp_f32_e32 v117, v117
	s_waitcnt lgkmcnt(8)
	v_mfma_f32_16x16x32_bf16 v[78:81], v[178:181], v[8:11], v[78:81]
	v_exp_f32_e32 v110, v110
	v_exp_f32_e32 v111, v111
	v_mfma_f32_16x16x32_bf16 v[90:93], v[170:173], v[16:19], v[90:93]
	v_exp_f32_e32 v112, v112
	v_exp_f32_e32 v113, v113
	v_mfma_f32_16x16x32_bf16 v[94:97], v[178:181], v[16:19], v[94:97]
	v_exp_f32_e32 v106, v106
	v_exp_f32_e32 v107, v107
	v_exp_f32_e32 v108, v108
	v_exp_f32_e32 v109, v109
	ds_read_b64 v[166:167], v214 offset:1088
	ds_read_b64 v[168:169], v214 offset:1120
	ds_read_b64 v[170:171], v215 offset:1344
	ds_read_b64 v[172:173], v215 offset:1376
	ds_read_b64 v[174:175], v216 offset:1600
	ds_read_b64 v[176:177], v216 offset:1632
	ds_read_b64 v[178:179], v217 offset:1088
	ds_read_b64 v[180:181], v217 offset:1120
	v_cvt_pk_bf16_f32 v186, v98, v99
	v_cvt_pk_bf16_f32 v187, v100, v101
	v_cvt_pk_bf16_f32 v188, v102, v103
	v_cvt_pk_bf16_f32 v189, v104, v105
	v_cvt_pk_bf16_f32 v190, v126, v127
	v_cvt_pk_bf16_f32 v191, v128, v129
	v_cvt_pk_bf16_f32 v192, v114, v115
	v_cvt_pk_bf16_f32 v193, v116, v117
	v_cvt_pk_bf16_f32 v194, v118, v119
	v_cvt_pk_bf16_f32 v195, v120, v121
	v_cvt_pk_bf16_f32 v196, v122, v123
	v_cvt_pk_bf16_f32 v197, v124, v125
	v_cvt_pk_bf16_f32 v182, v110, v111
	v_cvt_pk_bf16_f32 v183, v112, v113
	v_cvt_pk_bf16_f32 v184, v106, v107
	v_cvt_pk_bf16_f32 v185, v108, v109
	s_waitcnt lgkmcnt(14)
	v_mfma_f32_16x16x32_bf16 v[58:61], v[198:201], v[186:189], v[58:61]
	v_add_f32_e32 v0, 0, v98
	v_add_f32_e32 v2, 0, v126
	v_mfma_f32_16x16x32_bf16 v[42:45], v[198:201], v[190:193], v[42:45]
	v_add_f32_e32 v0, v99, v0
	v_add_f32_e32 v2, v127, v2
	s_waitcnt lgkmcnt(12)
	v_mfma_f32_16x16x32_bf16 v[54:57], v[202:205], v[186:189], v[54:57]
	v_add_f32_e32 v0, v100, v0
	v_add_f32_e32 v2, v128, v2
	v_mfma_f32_16x16x32_bf16 v[38:41], v[202:205], v[190:193], v[38:41]
	v_add_f32_e32 v0, v101, v0
	v_add_f32_e32 v2, v129, v2
	s_waitcnt lgkmcnt(10)
	v_mfma_f32_16x16x32_bf16 v[50:53], v[206:209], v[186:189], v[50:53]
	v_add_f32_e32 v0, v102, v0
	v_add_f32_e32 v2, v114, v2
	v_mfma_f32_16x16x32_bf16 v[34:37], v[206:209], v[190:193], v[34:37]
	v_add_f32_e32 v0, v103, v0
	v_add_f32_e32 v2, v115, v2
	s_waitcnt lgkmcnt(8)
	v_mfma_f32_16x16x32_bf16 v[46:49], v[210:213], v[186:189], v[46:49]
	v_add_f32_e32 v0, v104, v0
	v_add_f32_e32 v2, v116, v2
	v_mfma_f32_16x16x32_bf16 v[30:33], v[210:213], v[190:193], v[30:33]
	v_add_f32_e32 v0, v105, v0
	v_add_f32_e32 v2, v117, v2
	s_waitcnt lgkmcnt(6)
	v_mfma_f32_16x16x32_bf16 v[58:61], v[166:169], v[194:197], v[58:61]
	v_add_f32_e32 v0, v118, v0
	v_add_f32_e32 v2, v110, v2
	v_mfma_f32_16x16x32_bf16 v[42:45], v[166:169], v[182:185], v[42:45]
	v_add_f32_e32 v0, v119, v0
	v_add_f32_e32 v2, v111, v2
	s_waitcnt lgkmcnt(4)
	v_mfma_f32_16x16x32_bf16 v[54:57], v[170:173], v[194:197], v[54:57]
	v_add_f32_e32 v0, v120, v0
	v_add_f32_e32 v2, v112, v2
	v_mfma_f32_16x16x32_bf16 v[38:41], v[170:173], v[182:185], v[38:41]
	v_add_f32_e32 v0, v121, v0
	v_add_f32_e32 v2, v113, v2
	s_waitcnt lgkmcnt(2)
	v_mfma_f32_16x16x32_bf16 v[50:53], v[174:177], v[194:197], v[50:53]
	v_add_f32_e32 v0, v122, v0
	v_add_f32_e32 v2, v106, v2
	v_mfma_f32_16x16x32_bf16 v[34:37], v[174:177], v[182:185], v[34:37]
	v_add_f32_e32 v0, v123, v0
	v_add_f32_e32 v2, v107, v2
	s_waitcnt lgkmcnt(0)
	v_mfma_f32_16x16x32_bf16 v[46:49], v[178:181], v[194:197], v[46:49]
	v_add_f32_e32 v0, v124, v0
	v_add_f32_e32 v2, v108, v2
	v_mfma_f32_16x16x32_bf16 v[30:33], v[178:181], v[182:185], v[30:33]
	v_add_f32_e32 v0, v125, v0
	v_add_f32_e32 v2, v109, v2
	v_add_f32_e32 v163, v163, v0
	v_add_f32_e32 v162, v162, v2
	s_mov_b32 s32, 1
	s_branch .LBB0_888
; DI f32x4 mfma16(bf16x8 a, bf16x8 b, f32x4 c) { return __builtin_amdgcn_mfma_f32_16x16x32_bf16(a, b, c, 0, 0, 0); }
; DI void flash_s3(const u16* sK, const bf16x8 (&qf)[2][2], float si0, float si1, f32x4 (&s)[2][4], int lane) {
;   const int l15 = lane & 15, lg = lane >> 4;
;   bf16x8 kf[4][2];
; #pragma unroll
;   for (int kt = 0; kt < 4; ++kt)
; #pragma unroll
;     for (int ks = 0; ks < 2; ++ks) kf[kt][ks] = *(const bf16x8*)(sK + (16 * kt + l15) * 72 + ks * 32 + lg * 8);
; #pragma unroll
;   for (int qt = 0; qt < 2; ++qt) {
;     const float si = qt ? si1 : si0;
; #pragma unroll
;     for (int kt = 0; kt < 4; ++kt) {
;       s[qt][kt] = f32x4{si, si, si, si};
; #pragma unroll
;       for (int ks = 0; ks < 2; ++ks) s[qt][kt] = mfma16(kf[kt][ks], qf[qt][ks], s[qt][kt]);
;     }
;   }
; }
; template <bool MASKED, class MaskF>
; DI void flash_pv3(const u16* sV, const f32x4 (&s)[2][4], f32x4 (&O)[2][4], float (&l)[2], MaskF ok, int lane) {
;   const int l15 = lane & 15, lg = lane >> 4;
;   union PFrag { unsigned u[4]; bf16x8 v; };
;   PFrag pf[2][2];
; #pragma unroll
;   for (int qt = 0; qt < 2; ++qt) {
;     float pr[4][4];
;     float rs = 0.f;
; #pragma unroll
;     for (int kt = 0; kt < 4; ++kt)
; #pragma unroll
;       for (int i = 0; i < 4; ++i) {
;         float pv = __builtin_amdgcn_exp2f(s[qt][kt][i]);
;         if (MASKED) pv = ok(kt, i) ? pv : 0.f;
;         pr[kt][i] = pv;
;         rs += pv;
;       }
;     l[qt] += rs;
; #pragma unroll
;     for (int ks2 = 0; ks2 < 2; ++ks2) {
;       pf[qt][ks2].u[0] = pk2(pr[2 * ks2][0], pr[2 * ks2][1]);
;       pf[qt][ks2].u[1] = pk2(pr[2 * ks2][2], pr[2 * ks2][3]);
;       pf[qt][ks2].u[2] = pk2(pr[2 * ks2 + 1][0], pr[2 * ks2 + 1][1]);
;       pf[qt][ks2].u[3] = pk2(pr[2 * ks2 + 1][2], pr[2 * ks2 + 1][3]);
;     }
;   }
; #pragma unroll
;   for (int ks2 = 0; ks2 < 2; ++ks2) {
; #pragma unroll
;     for (int dt = 0; dt < 4; ++dt) {
;       union { uint2 h[2]; bf16x8 v; } vf;
;       vf.h[0] = *(const uint2*)(sV + (16 * dt + l15) * 72 + 32 * ks2 + 4 * lg);
;       vf.h[1] = *(const uint2*)(sV + (16 * dt + l15) * 72 + 32 * ks2 + 16 + 4 * lg);
;       O[0][dt] = mfma16(vf.v, pf[0][ks2].v, O[0][dt]);
;       O[1][dt] = mfma16(vf.v, pf[1][ks2].v, O[1][dt]);
;     }
;   }
; }
.Lmy_selC_fastB:
	v_lshrrev_b64 v[186:187], s42, v[20:21]
	v_lshrrev_b64 v[2:3], s42, v[22:23]
	s_cmp_lt_u32 s42, 64
	s_cselect_b64 s[36:37], -1, 0
	v_cndmask_b32_e64 v0, v2, v186, s[36:37]
	v_and_b32_e32 v0, 1, v0
	s_mul_i32 s36, s44, 0x4800
	v_cmp_eq_u32_e32 vcc, 1, v0
	v_add_u32_e32 v0, s36, v158
	v_lshl_add_u32 v2, v28, 1, v0
	ds_read_b128 v[126:129], v2
	ds_read_b128 v[114:117], v2 offset:64
	s_cmp_eq_u32 s42, s33
	ds_read_b128 v[110:113], v2 offset:2304
	ds_read_b128 v[106:109], v2 offset:2368
	s_cselect_b64 s[36:37], -1, 0
	s_or_b64 s[36:37], vcc, s[36:37]
	v_cndmask_b32_e64 v122, v148, -v29, s[36:37]
	v_lshl_add_u32 v0, v164, 1, v0
	v_cndmask_b32_e64 v182, v148, -v161, s[36:37]
	ds_read_b128 v[166:169], v2 offset:4608
	ds_read_b128 v[170:173], v2 offset:4672
	ds_read_b128 v[174:177], v0
	ds_read_b128 v[178:181], v0 offset:64
	v_mov_b32_e32 v123, v122
	v_mov_b32_e32 v124, v122
	v_mov_b32_e32 v125, v122
	v_mov_b32_e32 v183, v182
	v_mov_b32_e32 v184, v182
	v_mov_b32_e32 v185, v182
	s_mulk_i32 s45, 0x4800
	v_lshlrev_b32_e32 v160, 1, v28
	v_lshlrev_b32_e32 v3, 1, v164
	s_add_i32 s40, s45, 32
	v_add3_u32 v198, s40, v160, v159
	v_add3_u32 v206, s40, v3, v159
	v_add_u32_e32 v214, 0x2000, v198
	v_add_u32_e32 v215, 0x2800, v198
	v_add_u32_e32 v216, 0x3000, v198
	v_add_u32_e32 v217, 0x2000, v206
	v_exp_f32_e32 v66, v66
	v_exp_f32_e32 v67, v67
	v_exp_f32_e32 v68, v68
	v_exp_f32_e32 v69, v69
	v_exp_f32_e32 v70, v70
	v_exp_f32_e32 v71, v71
	s_waitcnt lgkmcnt(7)
	v_mfma_f32_16x16x32_bf16 v[98:101], v[126:129], v[4:7], v[122:125]
	v_exp_f32_e32 v72, v72
	v_mfma_f32_16x16x32_bf16 v[126:129], v[126:129], v[12:15], v[182:185]
	v_exp_f32_e32 v73, v73
	s_waitcnt lgkmcnt(6)
	v_mfma_f32_16x16x32_bf16 v[98:101], v[114:117], v[8:11], v[98:101]
	ds_read_b64 v[198:199], v214 offset:1024
	ds_read_b64 v[200:201], v214 offset:1056
	ds_read_b64 v[202:203], v215 offset:1280
	ds_read_b64 v[204:205], v215 offset:1312
	ds_read_b64 v[206:207], v216 offset:1536
	ds_read_b64 v[208:209], v216 offset:1568
	ds_read_b64 v[210:211], v217 offset:1024
	ds_read_b64 v[212:213], v217 offset:1056
	v_exp_f32_e32 v74, v74
	v_exp_f32_e32 v75, v75
	s_waitcnt lgkmcnt(13)
	v_mfma_f32_16x16x32_bf16 v[102:105], v[110:113], v[4:7], v[122:125]
	v_exp_f32_e32 v76, v76
	v_mfma_f32_16x16x32_bf16 v[126:129], v[114:117], v[16:19], v[126:129]
	v_exp_f32_e32 v77, v77
	v_mfma_f32_16x16x32_bf16 v[114:117], v[110:113], v[12:15], v[182:185]
	v_exp_f32_e32 v78, v78
	v_exp_f32_e32 v79, v79
	s_waitcnt lgkmcnt(12)
	v_mfma_f32_16x16x32_bf16 v[102:105], v[106:109], v[8:11], v[102:105]
	v_exp_f32_e32 v80, v80
	v_exp_f32_e32 v81, v81
	s_waitcnt lgkmcnt(11)
	v_mfma_f32_16x16x32_bf16 v[118:121], v[166:169], v[4:7], v[122:125]
	v_exp_f32_e32 v82, v82
	v_exp_f32_e32 v83, v83
	s_waitcnt lgkmcnt(9)
	v_mfma_f32_16x16x32_bf16 v[122:125], v[174:177], v[4:7], v[122:125]
	v_exp_f32_e32 v84, v84
	v_mfma_f32_16x16x32_bf16 v[114:117], v[106:109], v[16:19], v[114:117]
	v_exp_f32_e32 v85, v85
	v_mfma_f32_16x16x32_bf16 v[110:113], v[166:169], v[12:15], v[182:185]
	v_exp_f32_e32 v86, v86
	v_mfma_f32_16x16x32_bf16 v[106:109], v[174:177], v[12:15], v[182:185]
	v_exp_f32_e32 v87, v87
	v_mfma_f32_16x16x32_bf16 v[118:121], v[170:173], v[8:11], v[118:121]
	v_exp_f32_e32 v88, v88
	v_exp_f32_e32 v89, v89
	s_waitcnt lgkmcnt(8)
	v_mfma_f32_16x16x32_bf16 v[122:125], v[178:181], v[8:11], v[122:125]
	v_exp_f32_e32 v90, v90
	v_exp_f32_e32 v91, v91
	v_mfma_f32_16x16x32_bf16 v[110:113], v[170:173], v[16:19], v[110:113]
	v_exp_f32_e32 v92, v92
	v_exp_f32_e32 v93, v93
	v_mfma_f32_16x16x32_bf16 v[106:109], v[178:181], v[16:19], v[106:109]
	v_exp_f32_e32 v94, v94
	v_exp_f32_e32 v95, v95
	v_exp_f32_e32 v96, v96
	v_exp_f32_e32 v97, v97
	ds_read_b64 v[166:167], v214 offset:1088
	ds_read_b64 v[168:169], v214 offset:1120
	ds_read_b64 v[170:171], v215 offset:1344
	ds_read_b64 v[172:173], v215 offset:1376
	ds_read_b64 v[174:175], v216 offset:1600
	ds_read_b64 v[176:177], v216 offset:1632
	ds_read_b64 v[178:179], v217 offset:1088
	ds_read_b64 v[180:181], v217 offset:1120
	v_cvt_pk_bf16_f32 v186, v66, v67
	v_cvt_pk_bf16_f32 v187, v68, v69
	v_cvt_pk_bf16_f32 v188, v70, v71
	v_cvt_pk_bf16_f32 v189, v72, v73
	v_cvt_pk_bf16_f32 v190, v82, v83
	v_cvt_pk_bf16_f32 v191, v84, v85
	v_cvt_pk_bf16_f32 v192, v86, v87
	v_cvt_pk_bf16_f32 v193, v88, v89
	v_cvt_pk_bf16_f32 v194, v74, v75
	v_cvt_pk_bf16_f32 v195, v76, v77
	v_cvt_pk_bf16_f32 v196, v78, v79
	v_cvt_pk_bf16_f32 v197, v80, v81
	v_cvt_pk_bf16_f32 v182, v90, v91
	v_cvt_pk_bf16_f32 v183, v92, v93
	v_cvt_pk_bf16_f32 v184, v94, v95
	v_cvt_pk_bf16_f32 v185, v96, v97
	s_waitcnt lgkmcnt(14)
	v_mfma_f32_16x16x32_bf16 v[58:61], v[198:201], v[186:189], v[58:61]
	v_add_f32_e32 v0, 0, v66
	v_add_f32_e32 v2, 0, v82
	v_mfma_f32_16x16x32_bf16 v[42:45], v[198:201], v[190:193], v[42:45]
	v_add_f32_e32 v0, v67, v0
	v_add_f32_e32 v2, v83, v2
	s_waitcnt lgkmcnt(12)
	v_mfma_f32_16x16x32_bf16 v[54:57], v[202:205], v[186:189], v[54:57]
	v_add_f32_e32 v0, v68, v0
	v_add_f32_e32 v2, v84, v2
	v_mfma_f32_16x16x32_bf16 v[38:41], v[202:205], v[190:193], v[38:41]
	v_add_f32_e32 v0, v69, v0
	v_add_f32_e32 v2, v85, v2
	s_waitcnt lgkmcnt(10)
	v_mfma_f32_16x16x32_bf16 v[50:53], v[206:209], v[186:189], v[50:53]
	v_add_f32_e32 v0, v70, v0
	v_add_f32_e32 v2, v86, v2
	v_mfma_f32_16x16x32_bf16 v[34:37], v[206:209], v[190:193], v[34:37]
	v_add_f32_e32 v0, v71, v0
	v_add_f32_e32 v2, v87, v2
	s_waitcnt lgkmcnt(8)
	v_mfma_f32_16x16x32_bf16 v[46:49], v[210:213], v[186:189], v[46:49]
	v_add_f32_e32 v0, v72, v0
	v_add_f32_e32 v2, v88, v2
	v_mfma_f32_16x16x32_bf16 v[30:33], v[210:213], v[190:193], v[30:33]
	v_add_f32_e32 v0, v73, v0
	v_add_f32_e32 v2, v89, v2
	s_waitcnt lgkmcnt(6)
	v_mfma_f32_16x16x32_bf16 v[58:61], v[166:169], v[194:197], v[58:61]
	v_add_f32_e32 v0, v74, v0
	v_add_f32_e32 v2, v90, v2
	v_mfma_f32_16x16x32_bf16 v[42:45], v[166:169], v[182:185], v[42:45]
	v_add_f32_e32 v0, v75, v0
	v_add_f32_e32 v2, v91, v2
	s_waitcnt lgkmcnt(4)
	v_mfma_f32_16x16x32_bf16 v[54:57], v[170:173], v[194:197], v[54:57]
	v_add_f32_e32 v0, v76, v0
	v_add_f32_e32 v2, v92, v2
	v_mfma_f32_16x16x32_bf16 v[38:41], v[170:173], v[182:185], v[38:41]
	v_add_f32_e32 v0, v77, v0
	v_add_f32_e32 v2, v93, v2
	s_waitcnt lgkmcnt(2)
	v_mfma_f32_16x16x32_bf16 v[50:53], v[174:177], v[194:197], v[50:53]
	v_add_f32_e32 v0, v78, v0
	v_add_f32_e32 v2, v94, v2
	v_mfma_f32_16x16x32_bf16 v[34:37], v[174:177], v[182:185], v[34:37]
	v_add_f32_e32 v0, v79, v0
	v_add_f32_e32 v2, v95, v2
	s_waitcnt lgkmcnt(0)
	v_mfma_f32_16x16x32_bf16 v[46:49], v[178:181], v[194:197], v[46:49]
	v_add_f32_e32 v0, v80, v0
	v_add_f32_e32 v2, v96, v2
	v_mfma_f32_16x16x32_bf16 v[30:33], v[178:181], v[182:185], v[30:33]
	v_add_f32_e32 v0, v81, v0
	v_add_f32_e32 v2, v97, v2
	v_add_f32_e32 v163, v163, v0
	v_add_f32_e32 v162, v162, v2
	s_mov_b32 s32, 0
	s_branch .LBB0_888
